# m1st+m1pre: M1 C tile transposed through LDS and stored as 4 coalesced dwordx4/thread (was 32 two-byte stores); gate stage precomputed one item per wave
# speedup vs baseline: 1.0059x; 1.0059x over previous
;   __host__ __device__ __forceinline__ float* G() const { return (float*)(wsl() + OFF_G); }
;   __host__ __device__ __forceinline__ bf16_t* R() const { return (bf16_t*)(wsl() + OFF_R); }
; __device__ __forceinline__ int obid() { int t = blockIdx.x; asm volatile("" : "+s"(t)); return t; }
; __device__ __forceinline__ void m1_phase(const Params& p, char* smem) {
;     ...
;   bf16_t* Kt = (bf16_t*)smem;
;   bf16_t* Vt = Kt + 128 * 72;
;   float* wv = (float*)(Vt + 128 * 72);
;   for (int it = obid(); it < NCHAIN * NCHUNK; it += gridDim.x) {
;     int ci = it / NCHUNK, j = it - ci * NCHUNK;
;     int dir = ci & 1, h = (ci >> 1) & 3, b = ci >> 3;
;     int rowbase = b * TPB;
;     if (w == 0) {
;       int row = rowbase + mchunk_tok(dir, j, lane);
;       float gi = p.G()[(size_t)row * 16 + (2 * dir) * 4 + h] + p.mlstm_gate_b[(2 * dir) * 4 + h];
;       float gf = p.G()[(size_t)row * 16 + (2 * dir + 1) * 4 + h] + p.mlstm_gate_b[(2 * dir + 1) * 4 + h];
;     ...
;     bf16_t* dC = p.R() + (size_t)it * 16384;
; #pragma unroll
;     for (int ni = 0; ni < 8; ++ni)
; #pragma unroll
;       for (int jj = 0; jj < 4; ++jj) dC[(w * 16 + fq * 4 + jj) * 128 + ni * 16 + fr] = f2bf(acc[ni][jj]);
.LBB0_765:
	s_or_b64 exec, exec, s[4:5]
	s_mov_b32 s56, s82
	s_cmpk_gt_i32 s56, 0x83f
	s_cbranch_scc1 .LBB0_779
	s_waitcnt lgkmcnt(0)
	v_and_b32_e32 v1, 15, v8
	v_and_b32_e32 v0, 48, v10
	v_lshl_or_b32 v2, v18, 4, v1
	v_add_u32_e32 v0, 0, v0
	s_movk_i32 s4, 0x90
	v_mad_u64_u32 v[12:13], s[2:3], v2, s4, v[0:1]
	v_mul_lo_u32 v2, v8, s4
	v_add_u32_e32 v13, 0, v2
	v_ashrrev_i32_e32 v2, 3, v8
	v_and_b32_e32 v14, -8, v2
	s_movk_i32 s4, 0x48
	v_mul_lo_u32 v3, v14, s4
	v_lshl_add_u32 v11, v10, 2, 0
	v_or_b32_e32 v3, v3, v10
	v_or_b32_e32 v2, 7, v2
	v_lshl_add_u32 v38, v3, 1, 0
	v_mad_u64_u32 v[2:3], s[2:3], v2, s4, v[10:11]
	v_lshl_add_u32 v39, v2, 1, 0
	v_add_u32_e32 v2, 0x200, v8
	v_ashrrev_i32_e32 v2, 3, v2
	v_and_b32_e32 v16, -8, v2
	v_mul_lo_u32 v3, v16, s4
	v_or_b32_e32 v3, v3, v10
	v_or_b32_e32 v2, 7, v2
	v_lshl_add_u32 v40, v3, 1, 0
	v_mad_u64_u32 v[2:3], s[2:3], v2, s4, v[10:11]
	s_load_dwordx2 s[2:3], s[0:1], 0xf0
	v_lshl_add_u32 v41, v2, 1, 0
	v_lshlrev_b32_e32 v2, 5, v10
	v_lshlrev_b32_e32 v3, 11, v18
	s_movk_i32 s4, 0x600
	s_waitcnt lgkmcnt(0)
	s_add_u32 s58, s2, 0x7290000
	s_addc_u32 s59, s3, 0
	v_ashrrev_i32_e32 v9, 31, v8
	v_and_or_b32 v2, v2, s4, v3
	s_add_u32 s8, s2, 0xcd50000
	v_mul_u32_u24_e32 v4, 0x90, v1
	v_ashrrev_i32_e32 v19, 31, v2
	v_or_b32_e32 v20, v1, v2
	s_addc_u32 s9, s3, 0
	v_lshl_add_u64 v[2:3], v[8:9], 2, s[2:3]
	s_mov_b64 s[2:3], 0x113b7000
	v_cmp_gt_u32_e64 s[40:41], 64, v8
	v_cmp_eq_u32_e64 s[42:43], 0, v10
	v_cmp_gt_i32_e64 s[44:45], s85, v8
	v_cmp_gt_u32_e64 s[46:47], 2, v10
	v_cmp_gt_u32_e64 s[48:49], 4, v10
	v_cmp_gt_u32_e64 s[50:51], 8, v10
	v_cmp_gt_u32_e64 s[52:53], 16, v10
	v_cmp_gt_u32_e64 s[54:55], 32, v10
	v_ashrrev_i32_e32 v15, 31, v14
	v_ashrrev_i32_e32 v17, 31, v16
	v_ashrrev_i32_e32 v21, 31, v20
	v_lshl_add_u64 v[22:23], v[2:3], 0, s[2:3]
	v_mov_b32_e32 v18, v20
	v_or_b32_e32 v24, 16, v20
	v_mov_b32_e32 v25, v19
	v_or_b32_e32 v26, 32, v20
	v_mov_b32_e32 v27, v19
	v_or_b32_e32 v28, 48, v20
	v_mov_b32_e32 v29, v19
	v_or_b32_e32 v30, 64, v20
	v_mov_b32_e32 v31, v19
	v_or_b32_e32 v32, 0x50, v20
	v_mov_b32_e32 v33, v19
	v_or_b32_e32 v34, 0x60, v20
	v_mov_b32_e32 v35, v19
	v_or_b32_e32 v36, 0x70, v20
	v_mov_b32_e32 v37, v19
	v_add_u32_e32 v9, v0, v4
	v_lshrrev_b32_e32 v79, 6, v8
	v_lshrrev_b32_e32 v76, 4, v10
	v_lshl_add_u32 v76, v79, 2, v76
	v_mul_u32_u24_e32 v76, 0x440, v76
	v_and_b32_e32 v77, 15, v10
	v_lshl_add_u32 v76, v77, 1, v76
	v_add_u32_e32 v76, 0x9900, v76
	v_lshrrev_b32_e32 v78, 4, v10
	v_lshl_add_u32 v78, v79, 4, v78
	v_and_b32_e32 v79, 15, v10
	v_mul_u32_u24_e32 v77, 0x110, v78
	v_lshl_add_u32 v77, v79, 4, v77
	v_add_u32_e32 v77, 0x9900, v77
	v_lshlrev_b32_e32 v78, 8, v78
	v_lshl_add_u32 v78, v79, 4, v78
	v_mov_b32_e32 v79, 0
	s_mov_b32 s61, 0
	v_readfirstlane_b32 s62, v8
	s_lshr_b32 s62, s62, 6
	s_mul_i32 s63, s62, s80
	s_add_i32 s63, s63, s56
	s_lshl_b32 s64, s62, 8

;   __host__ __device__ __forceinline__ bf16_t* ACT() const { return (bf16_t*)(wsl() + OFF_ACT); }
; __device__ __forceinline__ float bf2f(bf16_t h) { return __uint_as_float(((uint32_t)h) << 16); }
; __device__ __forceinline__ void m1_phase(const Params& p, char* smem) {
;     ...
; #pragma unroll
;     for (int i = 0; i < 2; ++i) {
;       int idx = tid + i * NTHR;
;       int r = idx & 63, fc = (idx >> 6) * 8;
;       int row = rowbase + mchunk_tok(dir, j, r);
;       const bf16_t* src = p.ACT() + (size_t)row * PW;
;       uint4 kv = *(const uint4*)(src + 1184 + h * 128 + fc);
;       uint4 vv = *(const uint4*)(src + 1696 + h * 128 + fc);
;       float wr = wv[r];
;       const bf16_t* ke = (const bf16_t*)&kv; const bf16_t* ve = (const bf16_t*)&vv;
; #pragma unroll
;       for (int e = 0; e < 8; ++e) {
;         Kt[(fc + e) * 72 + r] = ke[e];
;         Vt[(fc + e) * 72 + r] = f2bf(bf2f(ve[e]) * wr);
;       }
;     }
;     __syncthreads();
.LBB0_775:
	s_cmp_eq_u32 s13, 0
	s_cselect_b64 vcc, -1, 0
	s_cmp_gt_i32 s12, 3
	s_cselect_b32 s2, 0x87, 3
	s_sub_i32 s2, s2, s12
	s_lshl_b32 s2, s2, 6
	v_bitop3_b32 v0, s2, 63, v10 bitop3:0x36
	v_lshl_or_b32 v1, s12, 6, v10
	v_cndmask_b32_e32 v0, v0, v1, vcc
	v_add_u32_e32 v2, s11, v0
	v_mov_b64_e32 v[0:1], s[58:59]
	v_mad_i64_i32 v[0:1], s[2:3], v2, s84, v[0:1]
	s_lshl_b32 s30, s10, 8
	v_lshl_add_u64 v[44:45], v[0:1], 0, s[30:31]
	v_lshl_add_u64 v[4:5], v[14:15], 1, v[44:45]
	s_waitcnt vmcnt(0) lgkmcnt(0)
	s_barrier
	v_add_u32_e32 v74, s61, v11
	ds_read_b32 v42, v74 offset:36864
	global_load_dwordx4 v[0:3], v[4:5], off offset:2368
	s_nop 0
	global_load_dwordx4 v[4:7], v[4:5], off offset:3392
	s_ashr_i32 s57, s56, 31
	s_lshl_b64 s[2:3], s[56:57], 15
	s_add_u32 s4, s8, s2
	s_addc_u32 s5, s9, s3
	s_waitcnt vmcnt(1)
	ds_write_b16 v38, v0
	s_waitcnt vmcnt(0)
	v_lshlrev_b32_e32 v43, 16, v4
	s_waitcnt lgkmcnt(1)
	v_mul_f32_e32 v43, v42, v43
	v_bfe_u32 v46, v43, 16, 1
	v_add3_u32 v43, v43, v46, s28
	ds_write_b16_d16_hi v38, v43 offset:18432
	ds_write_b16_d16_hi v38, v0 offset:144
	v_and_b32_e32 v0, 0xffff0000, v4
	v_mul_f32_e32 v0, v42, v0
	v_bfe_u32 v4, v0, 16, 1
	v_add3_u32 v0, v0, v4, s28
	ds_write_b16_d16_hi v38, v0 offset:18576
	ds_write_b16 v38, v1 offset:288
	v_lshlrev_b32_e32 v0, 16, v5
	v_mul_f32_e32 v0, v42, v0
	v_bfe_u32 v4, v0, 16, 1
	v_add3_u32 v0, v0, v4, s28
	ds_write_b16_d16_hi v38, v0 offset:18720
	ds_write_b16_d16_hi v38, v1 offset:432
	v_and_b32_e32 v0, 0xffff0000, v5
	v_mul_f32_e32 v0, v42, v0
	v_bfe_u32 v1, v0, 16, 1
	v_add3_u32 v0, v0, v1, s28
	ds_write_b16_d16_hi v38, v0 offset:18864
	ds_write_b16 v38, v2 offset:576
	v_lshlrev_b32_e32 v0, 16, v6
	v_mul_f32_e32 v0, v42, v0
	v_bfe_u32 v1, v0, 16, 1
	v_add3_u32 v0, v0, v1, s28
	ds_write_b16_d16_hi v38, v0 offset:19008
	ds_write_b16_d16_hi v38, v2 offset:720
	v_and_b32_e32 v0, 0xffff0000, v6
	v_mul_f32_e32 v0, v42, v0
	v_bfe_u32 v1, v0, 16, 1
	v_add3_u32 v0, v0, v1, s28
	ds_write_b16_d16_hi v38, v0 offset:19152
	ds_write_b16 v38, v3 offset:864
	v_lshlrev_b32_e32 v0, 16, v7
	v_mul_f32_e32 v0, v42, v0
	v_bfe_u32 v1, v0, 16, 1
	v_add3_u32 v0, v0, v1, s28
	ds_write_b16_d16_hi v38, v0 offset:19296
	ds_write_b16_d16_hi v39, v3
	v_and_b32_e32 v0, 0xffff0000, v7
	v_mul_f32_e32 v0, v42, v0
	v_bfe_u32 v1, v0, 16, 1
	v_add3_u32 v0, v0, v1, s28
	ds_write_b16_d16_hi v39, v0 offset:18432
	v_lshl_add_u64 v[4:5], v[16:17], 1, v[44:45]
	global_load_dwordx4 v[0:3], v[4:5], off offset:2368
	s_nop 0
	global_load_dwordx4 v[4:7], v[4:5], off offset:3392
	s_waitcnt vmcnt(1)
	ds_write_b16 v40, v0
	s_waitcnt vmcnt(0)
	v_lshlrev_b32_e32 v43, 16, v4
	v_mul_f32_e32 v43, v42, v43
	v_bfe_u32 v44, v43, 16, 1
	v_add3_u32 v43, v43, v44, s28
	ds_write_b16_d16_hi v40, v43 offset:18432
	ds_write_b16_d16_hi v40, v0 offset:144
	v_and_b32_e32 v0, 0xffff0000, v4
	v_mul_f32_e32 v0, v42, v0
	v_bfe_u32 v4, v0, 16, 1
	v_add3_u32 v0, v0, v4, s28
	ds_write_b16_d16_hi v40, v0 offset:18576
	ds_write_b16 v40, v1 offset:288
	v_lshlrev_b32_e32 v0, 16, v5
	v_mul_f32_e32 v0, v42, v0
	v_bfe_u32 v4, v0, 16, 1
	v_add3_u32 v0, v0, v4, s28
	ds_write_b16_d16_hi v40, v0 offset:18720
	ds_write_b16_d16_hi v40, v1 offset:432
	v_and_b32_e32 v0, 0xffff0000, v5
	v_mul_f32_e32 v0, v42, v0
	v_bfe_u32 v1, v0, 16, 1
	v_add3_u32 v0, v0, v1, s28
	ds_write_b16_d16_hi v40, v0 offset:18864
	ds_write_b16 v40, v2 offset:576
	v_lshlrev_b32_e32 v0, 16, v6
	v_mul_f32_e32 v0, v42, v0
	v_bfe_u32 v1, v0, 16, 1
	v_add3_u32 v0, v0, v1, s28
	ds_write_b16_d16_hi v40, v0 offset:19008
	ds_write_b16_d16_hi v40, v2 offset:720
	v_and_b32_e32 v0, 0xffff0000, v6
	v_mul_f32_e32 v0, v42, v0
	v_bfe_u32 v1, v0, 16, 1
	v_add3_u32 v0, v0, v1, s28
	ds_write_b16_d16_hi v40, v0 offset:19152
	ds_write_b16 v40, v3 offset:864
	v_lshlrev_b32_e32 v0, 16, v7
	v_mul_f32_e32 v0, v42, v0
	v_bfe_u32 v1, v0, 16, 1
	v_add3_u32 v0, v0, v1, s28
	ds_write_b16_d16_hi v40, v0 offset:19296
	ds_write_b16_d16_hi v41, v3
	v_and_b32_e32 v0, 0xffff0000, v7
	v_mul_f32_e32 v0, v42, v0
	v_bfe_u32 v1, v0, 16, 1
	v_add3_u32 v0, v0, v1, s28
	ds_write_b16_d16_hi v41, v0 offset:18432
	s_waitcnt lgkmcnt(0)
	s_barrier
;   __host__ __device__ __forceinline__ bf16_t* R() const { return (bf16_t*)(wsl() + OFF_R); }
; #define MFMA16(a, b, c) __builtin_amdgcn_mfma_f32_16x16x32_bf16(a, b, c, 0, 0, 0)
; __device__ __forceinline__ void m1_phase(const Params& p, char* smem) {
;     ...
;     f32x4 acc[8];
; #pragma unroll
;     for (int ni = 0; ni < 8; ++ni) acc[ni] = (f32x4){0.f, 0.f, 0.f, 0.f};
; #pragma unroll
;     for (int ks = 0; ks < 2; ++ks) {
;       bf16x8 a = *(const bf16x8*)(Vt + (w * 16 + fr) * 72 + ks * 32 + fq * 8);
; #pragma unroll
;       for (int ni = 0; ni < 8; ++ni) {
;         bf16x8 bb = *(const bf16x8*)(Kt + (ni * 16 + fr) * 72 + ks * 32 + fq * 8);
;         acc[ni] = MFMA16(a, bb, acc[ni]);
;       }
;     }
;     bf16_t* dC = p.R() + (size_t)it * 16384;
; #pragma unroll
;     for (int ni = 0; ni < 8; ++ni)
; #pragma unroll
;       for (int jj = 0; jj < 4; ++jj) dC[(w * 16 + fq * 4 + jj) * 128 + ni * 16 + fr] = f2bf(acc[ni][jj]);
	ds_read_b128 v[0:3], v12 offset:18432
	ds_read_b128 v[4:7], v9
	ds_read_b128 v[42:45], v9 offset:2304
	ds_read_b128 v[46:49], v9 offset:4608
	ds_read_b128 v[50:53], v9 offset:6912
	ds_read_b128 v[54:57], v9 offset:9216
	ds_read_b128 v[58:61], v9 offset:11520
	ds_read_b128 v[62:65], v9 offset:13824
	ds_read_b128 v[66:69], v9 offset:16128
	s_waitcnt lgkmcnt(7)
	v_mfma_f32_16x16x32_bf16 v[4:7], v[0:3], v[4:7], 0
	s_waitcnt lgkmcnt(6)
	v_mfma_f32_16x16x32_bf16 v[42:45], v[0:3], v[42:45], 0
	s_waitcnt lgkmcnt(5)
	v_mfma_f32_16x16x32_bf16 v[46:49], v[0:3], v[46:49], 0
	s_waitcnt lgkmcnt(4)
	v_mfma_f32_16x16x32_bf16 v[50:53], v[0:3], v[50:53], 0
	s_waitcnt lgkmcnt(3)
	v_mfma_f32_16x16x32_bf16 v[54:57], v[0:3], v[54:57], 0
	s_waitcnt lgkmcnt(2)
	v_mfma_f32_16x16x32_bf16 v[58:61], v[0:3], v[58:61], 0
	s_waitcnt lgkmcnt(1)
	v_mfma_f32_16x16x32_bf16 v[62:65], v[0:3], v[62:65], 0
	s_waitcnt lgkmcnt(0)
	v_mfma_f32_16x16x32_bf16 v[0:3], v[0:3], v[66:69], 0
	ds_read_b128 v[66:69], v12 offset:18496
	ds_read_b128 v[70:73], v9 offset:64
	s_waitcnt lgkmcnt(0)
	v_mfma_f32_16x16x32_bf16 v[4:7], v[66:69], v[70:73], v[4:7]
	ds_read_b128 v[70:73], v9 offset:2368
	s_waitcnt lgkmcnt(0)
	v_mfma_f32_16x16x32_bf16 v[42:45], v[66:69], v[70:73], v[42:45]
	ds_read_b128 v[70:73], v9 offset:4672
	s_waitcnt lgkmcnt(0)
	v_mfma_f32_16x16x32_bf16 v[46:49], v[66:69], v[70:73], v[46:49]
	ds_read_b128 v[70:73], v9 offset:6976
	s_waitcnt lgkmcnt(0)
	v_mfma_f32_16x16x32_bf16 v[50:53], v[66:69], v[70:73], v[50:53]
	ds_read_b128 v[70:73], v9 offset:9280
	s_waitcnt lgkmcnt(0)
	v_mfma_f32_16x16x32_bf16 v[54:57], v[66:69], v[70:73], v[54:57]
	ds_read_b128 v[70:73], v9 offset:11584
	s_waitcnt lgkmcnt(0)
	v_mfma_f32_16x16x32_bf16 v[58:61], v[66:69], v[70:73], v[58:61]
	ds_read_b128 v[70:73], v9 offset:13888
	s_waitcnt lgkmcnt(0)
	v_mfma_f32_16x16x32_bf16 v[62:65], v[66:69], v[70:73], v[62:65]
	ds_read_b128 v[70:73], v9 offset:16192
	s_waitcnt lgkmcnt(0)
	v_mfma_f32_16x16x32_bf16 v[0:3], v[66:69], v[70:73], v[0:3]
	v_bfe_u32 v66, v4, 16, 1
	v_add3_u32 v66, v4, v66, s28
	ds_write_b16_d16_hi v76, v66 offset:0
	v_bfe_u32 v66, v5, 16, 1
	v_add3_u32 v66, v5, v66, s28
	ds_write_b16_d16_hi v76, v66 offset:272
	v_bfe_u32 v66, v6, 16, 1
	v_add3_u32 v66, v6, v66, s28
	ds_write_b16_d16_hi v76, v66 offset:544
	v_bfe_u32 v66, v7, 16, 1
	v_add3_u32 v66, v7, v66, s28
	ds_write_b16_d16_hi v76, v66 offset:816
	v_bfe_u32 v66, v42, 16, 1
	v_add3_u32 v66, v42, v66, s28
	ds_write_b16_d16_hi v76, v66 offset:32
	v_bfe_u32 v66, v43, 16, 1
	v_add3_u32 v66, v43, v66, s28
	ds_write_b16_d16_hi v76, v66 offset:304
	v_bfe_u32 v66, v44, 16, 1
	v_add3_u32 v66, v44, v66, s28
	ds_write_b16_d16_hi v76, v66 offset:576
	v_bfe_u32 v66, v45, 16, 1
	v_add3_u32 v66, v45, v66, s28
	ds_write_b16_d16_hi v76, v66 offset:848
	v_bfe_u32 v66, v46, 16, 1
	v_add3_u32 v66, v46, v66, s28
	ds_write_b16_d16_hi v76, v66 offset:64
	v_bfe_u32 v66, v47, 16, 1
	v_add3_u32 v66, v47, v66, s28
	ds_write_b16_d16_hi v76, v66 offset:336
	v_bfe_u32 v66, v48, 16, 1
	v_add3_u32 v66, v48, v66, s28
	ds_write_b16_d16_hi v76, v66 offset:608
	v_bfe_u32 v66, v49, 16, 1
	v_add3_u32 v66, v49, v66, s28
	ds_write_b16_d16_hi v76, v66 offset:880
	v_bfe_u32 v66, v50, 16, 1
	v_add3_u32 v66, v50, v66, s28
	ds_write_b16_d16_hi v76, v66 offset:96
	v_bfe_u32 v66, v51, 16, 1
	v_add3_u32 v66, v51, v66, s28
	ds_write_b16_d16_hi v76, v66 offset:368
	v_bfe_u32 v66, v52, 16, 1
	v_add3_u32 v66, v52, v66, s28
	ds_write_b16_d16_hi v76, v66 offset:640
	v_bfe_u32 v66, v53, 16, 1
	v_add3_u32 v66, v53, v66, s28
	ds_write_b16_d16_hi v76, v66 offset:912
	v_bfe_u32 v66, v54, 16, 1
	v_add3_u32 v66, v54, v66, s28
	ds_write_b16_d16_hi v76, v66 offset:128
	v_bfe_u32 v66, v55, 16, 1
	v_add3_u32 v66, v55, v66, s28
	ds_write_b16_d16_hi v76, v66 offset:400
	v_bfe_u32 v66, v56, 16, 1
	v_add3_u32 v66, v56, v66, s28
	ds_write_b16_d16_hi v76, v66 offset:672
	v_bfe_u32 v66, v57, 16, 1
	v_add3_u32 v66, v57, v66, s28
	ds_write_b16_d16_hi v76, v66 offset:944
	v_bfe_u32 v66, v58, 16, 1
	v_add3_u32 v66, v58, v66, s28
	ds_write_b16_d16_hi v76, v66 offset:160
	v_bfe_u32 v66, v59, 16, 1
	v_add3_u32 v66, v59, v66, s28
	ds_write_b16_d16_hi v76, v66 offset:432
	v_bfe_u32 v66, v60, 16, 1
	v_add3_u32 v66, v60, v66, s28
	ds_write_b16_d16_hi v76, v66 offset:704
	v_bfe_u32 v66, v61, 16, 1
	v_add3_u32 v66, v61, v66, s28
	ds_write_b16_d16_hi v76, v66 offset:976
	v_bfe_u32 v66, v62, 16, 1
	v_add3_u32 v66, v62, v66, s28
	ds_write_b16_d16_hi v76, v66 offset:192
	v_bfe_u32 v66, v63, 16, 1
	v_add3_u32 v66, v63, v66, s28
	ds_write_b16_d16_hi v76, v66 offset:464
	v_bfe_u32 v66, v64, 16, 1
	v_add3_u32 v66, v64, v66, s28
	ds_write_b16_d16_hi v76, v66 offset:736
	v_bfe_u32 v66, v65, 16, 1
	v_add3_u32 v66, v65, v66, s28
	ds_write_b16_d16_hi v76, v66 offset:1008
	v_bfe_u32 v66, v0, 16, 1
	v_add3_u32 v66, v0, v66, s28
	ds_write_b16_d16_hi v76, v66 offset:224
	v_bfe_u32 v66, v1, 16, 1
	v_add3_u32 v66, v1, v66, s28
	ds_write_b16_d16_hi v76, v66 offset:496
	v_bfe_u32 v66, v2, 16, 1
	v_add3_u32 v66, v2, v66, s28
	ds_write_b16_d16_hi v76, v66 offset:768
	v_bfe_u32 v66, v3, 16, 1
	v_add3_u32 v66, v3, v66, s28
	ds_write_b16_d16_hi v76, v66 offset:1040
	v_lshl_add_u64 v[96:97], v[78:79], 0, s[4:5]
	s_waitcnt lgkmcnt(0)
	ds_read_b128 v[80:83], v77 offset:0
	ds_read_b128 v[84:87], v77 offset:1088
	ds_read_b128 v[88:91], v77 offset:2176
	ds_read_b128 v[92:95], v77 offset:3264
	s_waitcnt lgkmcnt(3)
	global_store_dwordx4 v[96:97], v[80:83], off offset:0
	s_waitcnt lgkmcnt(2)
	global_store_dwordx4 v[96:97], v[84:87], off offset:1024
	s_waitcnt lgkmcnt(1)
	global_store_dwordx4 v[96:97], v[88:91], off offset:2048
	s_waitcnt lgkmcnt(0)
	global_store_dwordx4 v[96:97], v[92:95], off offset:3072
	s_and_saveexec_b64 s[4:5], s[44:45]
	s_cbranch_execz .LBB0_767
	s_add_i32 s2, s61, 0x9000
	v_mov_b32_e32 v0, 0
	s_mov_b32 s3, 0
